# grid barrier: XCD leader no longer waits for its release atomics to be acknowledged (waits only served the moved invalidate)
# speedup vs baseline: 1.0155x; 1.0033x over previous
.LBB0_72:
	s_or_b64 exec, exec, s[6:7]
	s_mov_b64 s[6:7], exec
	v_mbcnt_lo_u32_b32 v1, s6, 0
	v_mbcnt_hi_u32_b32 v1, s7, v1
	v_cmp_eq_u32_e32 vcc, 0, v1
	s_and_saveexec_b64 s[12:13], vcc
	s_cbranch_execz .LBB0_74
	s_bcnt1_i32_b64 s6, s[6:7]
	v_mov_b32_e32 v1, s6
	v_readlane_b32 s6, v252, 62
	v_readlane_b32 s7, v252, 63
	s_nop 4
	global_atomic_add v3, v1, s[6:7]
.LBB0_74:
	s_or_b64 exec, exec, s[12:13]
.LBB0_75:
	s_or_b64 exec, exec, s[4:5]
	s_waitcnt lgkmcnt(0)
	s_barrier
